# prompt pool units: window-sum loops software-pipelined two deep (two LDS reads in flight, second buffer v240-243)
# baseline (speedup 1.0000x reference)
.LBB0_643:
	ds_read_b128 v[148:151], v146
	v_add_u32_e32 v146, 0xfffffee0, v146
	ds_read_b128 v[240:243], v146
	v_add_u32_e32 v146, 0xfffffee0, v146
.Lws0_loop:
	s_waitcnt lgkmcnt(1)
	v_and_b32_e32 v153, 0xffff0000, v148
	v_and_b32_e32 v155, 0xffff0000, v149
	v_and_b32_e32 v157, 0xffff0000, v150
	v_and_b32_e32 v159, 0xffff0000, v151
	v_lshlrev_b32_e32 v152, 16, v148
	v_lshlrev_b32_e32 v154, 16, v149
	v_lshlrev_b32_e32 v156, 16, v150
	v_lshlrev_b32_e32 v158, 16, v151
	ds_read_b128 v[148:151], v146
	v_add_u32_e32 v146, 0xfffffee0, v146
	v_pk_add_f32 v[132:133], v[132:133], v[158:159]
	v_pk_add_f32 v[140:141], v[140:141], v[156:157]
	v_pk_add_f32 v[142:143], v[142:143], v[154:155]
	v_pk_add_f32 v[144:145], v[144:145], v[152:153]
	s_add_i32 s0, s0, -1
	s_cmp_eq_u32 s0, 0
	s_cbranch_scc1 .Lws0_exit
	s_waitcnt lgkmcnt(1)
	v_and_b32_e32 v153, 0xffff0000, v240
	v_and_b32_e32 v155, 0xffff0000, v241
	v_and_b32_e32 v157, 0xffff0000, v242
	v_and_b32_e32 v159, 0xffff0000, v243
	v_lshlrev_b32_e32 v152, 16, v240
	v_lshlrev_b32_e32 v154, 16, v241
	v_lshlrev_b32_e32 v156, 16, v242
	v_lshlrev_b32_e32 v158, 16, v243
	ds_read_b128 v[240:243], v146
	v_add_u32_e32 v146, 0xfffffee0, v146
	v_pk_add_f32 v[132:133], v[132:133], v[158:159]
	v_pk_add_f32 v[140:141], v[140:141], v[156:157]
	v_pk_add_f32 v[142:143], v[142:143], v[154:155]
	v_pk_add_f32 v[144:145], v[144:145], v[152:153]
	s_add_i32 s0, s0, -1
	s_cmp_eq_u32 s0, 0
	s_cbranch_scc0 .Lws0_loop
.Lws0_exit:
	s_waitcnt lgkmcnt(0)
	s_branch .LBB0_649

.LBB0_651:
	ds_read_b128 v[164:167], v162
	v_add_u32_e32 v162, 0xfffffee0, v162
	ds_read_b128 v[240:243], v162
	v_add_u32_e32 v162, 0xfffffee0, v162
.Lws1_loop:
	s_waitcnt lgkmcnt(1)
	v_and_b32_e32 v169, 0xffff0000, v164
	v_and_b32_e32 v171, 0xffff0000, v165
	v_and_b32_e32 v173, 0xffff0000, v166
	v_and_b32_e32 v175, 0xffff0000, v167
	v_lshlrev_b32_e32 v168, 16, v164
	v_lshlrev_b32_e32 v170, 16, v165
	v_lshlrev_b32_e32 v172, 16, v166
	v_lshlrev_b32_e32 v174, 16, v167
	ds_read_b128 v[164:167], v162
	v_add_u32_e32 v162, 0xfffffee0, v162
	v_pk_add_f32 v[146:147], v[146:147], v[174:175]
	v_pk_add_f32 v[156:157], v[156:157], v[172:173]
	v_pk_add_f32 v[158:159], v[158:159], v[170:171]
	v_pk_add_f32 v[160:161], v[160:161], v[168:169]
	s_add_i32 s25, s25, -1
	s_cmp_eq_u32 s25, 0
	s_cbranch_scc1 .Lws1_exit
	s_waitcnt lgkmcnt(1)
	v_and_b32_e32 v169, 0xffff0000, v240
	v_and_b32_e32 v171, 0xffff0000, v241
	v_and_b32_e32 v173, 0xffff0000, v242
	v_and_b32_e32 v175, 0xffff0000, v243
	v_lshlrev_b32_e32 v168, 16, v240
	v_lshlrev_b32_e32 v170, 16, v241
	v_lshlrev_b32_e32 v172, 16, v242
	v_lshlrev_b32_e32 v174, 16, v243
	ds_read_b128 v[240:243], v162
	v_add_u32_e32 v162, 0xfffffee0, v162
	v_pk_add_f32 v[146:147], v[146:147], v[174:175]
	v_pk_add_f32 v[156:157], v[156:157], v[172:173]
	v_pk_add_f32 v[158:159], v[158:159], v[170:171]
	v_pk_add_f32 v[160:161], v[160:161], v[168:169]
	s_add_i32 s25, s25, -1
	s_cmp_eq_u32 s25, 0
	s_cbranch_scc0 .Lws1_loop
.Lws1_exit:
	s_waitcnt lgkmcnt(0)
	s_and_b64 vcc, exec, s[0:1]
	s_cbranch_vccnz .LBB0_657

.LBB0_654:
	ds_read_b128 v[190:193], v189
	v_add_u32_e32 v189, 0xfffffee0, v189
	ds_read_b128 v[240:243], v189
	v_add_u32_e32 v189, 0xfffffee0, v189
.Lws2_loop:
	s_waitcnt lgkmcnt(1)
	v_and_b32_e32 v195, 0xffff0000, v190
	v_and_b32_e32 v197, 0xffff0000, v191
	v_and_b32_e32 v199, 0xffff0000, v192
	v_and_b32_e32 v201, 0xffff0000, v193
	v_lshlrev_b32_e32 v194, 16, v190
	v_lshlrev_b32_e32 v196, 16, v191
	v_lshlrev_b32_e32 v198, 16, v192
	v_lshlrev_b32_e32 v200, 16, v193
	ds_read_b128 v[190:193], v189
	v_add_u32_e32 v189, 0xfffffee0, v189
	v_pk_add_f32 v[162:163], v[162:163], v[200:201]
	v_pk_add_f32 v[172:173], v[172:173], v[198:199]
	v_pk_add_f32 v[174:175], v[174:175], v[196:197]
	v_pk_add_f32 v[186:187], v[186:187], v[194:195]
	s_add_i32 s25, s25, -1
	s_cmp_eq_u32 s25, 0
	s_cbranch_scc1 .Lws2_exit
	s_waitcnt lgkmcnt(1)
	v_and_b32_e32 v195, 0xffff0000, v240
	v_and_b32_e32 v197, 0xffff0000, v241
	v_and_b32_e32 v199, 0xffff0000, v242
	v_and_b32_e32 v201, 0xffff0000, v243
	v_lshlrev_b32_e32 v194, 16, v240
	v_lshlrev_b32_e32 v196, 16, v241
	v_lshlrev_b32_e32 v198, 16, v242
	v_lshlrev_b32_e32 v200, 16, v243
	ds_read_b128 v[240:243], v189
	v_add_u32_e32 v189, 0xfffffee0, v189
	v_pk_add_f32 v[162:163], v[162:163], v[200:201]
	v_pk_add_f32 v[172:173], v[172:173], v[198:199]
	v_pk_add_f32 v[174:175], v[174:175], v[196:197]
	v_pk_add_f32 v[186:187], v[186:187], v[194:195]
	s_add_i32 s25, s25, -1
	s_cmp_eq_u32 s25, 0
	s_cbranch_scc0 .Lws2_loop
.Lws2_exit:
	s_waitcnt lgkmcnt(0)
	s_and_b64 vcc, exec, s[0:1]
	s_cbranch_vccz .LBB0_658
	s_branch .LBB0_554

.LBB0_659:
	ds_read_b128 v[212:215], v0
	v_add_u32_e32 v0, 0xfffffee0, v0
	ds_read_b128 v[240:243], v0
	v_add_u32_e32 v0, 0xfffffee0, v0
.Lws3_loop:
	s_waitcnt lgkmcnt(1)
	v_and_b32_e32 v227, 0xffff0000, v212
	v_and_b32_e32 v229, 0xffff0000, v213
	v_and_b32_e32 v231, 0xffff0000, v214
	v_and_b32_e32 v233, 0xffff0000, v215
	v_lshlrev_b32_e32 v226, 16, v212
	v_lshlrev_b32_e32 v228, 16, v213
	v_lshlrev_b32_e32 v230, 16, v214
	v_lshlrev_b32_e32 v232, 16, v215
	ds_read_b128 v[212:215], v0
	v_add_u32_e32 v0, 0xfffffee0, v0
	v_pk_add_f32 v[190:191], v[190:191], v[232:233]
	v_pk_add_f32 v[198:199], v[198:199], v[230:231]
	v_pk_add_f32 v[200:201], v[200:201], v[228:229]
	v_pk_add_f32 v[202:203], v[202:203], v[226:227]
	s_add_i32 s0, s0, -1
	s_cmp_eq_u32 s0, 0
	s_cbranch_scc1 .Lws3_exit
	s_waitcnt lgkmcnt(1)
	v_and_b32_e32 v227, 0xffff0000, v240
	v_and_b32_e32 v229, 0xffff0000, v241
	v_and_b32_e32 v231, 0xffff0000, v242
	v_and_b32_e32 v233, 0xffff0000, v243
	v_lshlrev_b32_e32 v226, 16, v240
	v_lshlrev_b32_e32 v228, 16, v241
	v_lshlrev_b32_e32 v230, 16, v242
	v_lshlrev_b32_e32 v232, 16, v243
	ds_read_b128 v[240:243], v0
	v_add_u32_e32 v0, 0xfffffee0, v0
	v_pk_add_f32 v[190:191], v[190:191], v[232:233]
	v_pk_add_f32 v[198:199], v[198:199], v[230:231]
	v_pk_add_f32 v[200:201], v[200:201], v[228:229]
	v_pk_add_f32 v[202:203], v[202:203], v[226:227]
	s_add_i32 s0, s0, -1
	s_cmp_eq_u32 s0, 0
	s_cbranch_scc0 .Lws3_loop
